# S5 stage-3 epilogue: four gelu chains interleaved (171 -> 128 instructions per iteration, no s_nop pads)
# speedup vs baseline: 1.0064x; 1.0050x over previous
.Ls5_epi:
	s_nop 2
	v_lshlrev_b32_e32 v250, 16, v162
	v_and_b32_e32 v251, 0xffff0000, v162
	v_lshlrev_b32_e32 v246, 16, v163
	v_and_b32_e32 v247, 0xffff0000, v163
	v_mov_b64_e32 v[248:249], s[54:55]
	v_add_u32_e32 v158, 0x200, v158
	v_add_u32_e32 v159, 0x200, v159
	s_nop 1
	v_pk_fma_f32 v[224:225], v[8:9], v[250:251], v[100:101]
	v_pk_fma_f32 v[232:233], v[10:11], v[246:247], v[102:103]
	v_lshlrev_b32_e32 v250, 16, v168
	v_and_b32_e32 v251, 0xffff0000, v168
	v_lshlrev_b32_e32 v246, 16, v169
	v_and_b32_e32 v247, 0xffff0000, v169
	s_nop 0
	v_pk_fma_f32 v[92:93], v[8:9], v[250:251], v[88:89]
	v_pk_fma_f32 v[100:101], v[10:11], v[246:247], v[90:91]
	v_and_b32_e32 v226, 0x7fffffff, v224
	v_and_b32_e32 v227, 0x7fffffff, v225
	v_and_b32_e32 v234, 0x7fffffff, v232
	v_and_b32_e32 v235, 0x7fffffff, v233
	v_and_b32_e32 v94, 0x7fffffff, v92
	v_and_b32_e32 v95, 0x7fffffff, v93
	v_and_b32_e32 v102, 0x7fffffff, v100
	v_and_b32_e32 v103, 0x7fffffff, v101
	v_pk_fma_f32 v[226:227], v[226:227], s[80:81], 1.0 op_sel_hi:[1,0,0]
	v_pk_fma_f32 v[234:235], v[234:235], s[80:81], 1.0 op_sel_hi:[1,0,0]
	v_pk_fma_f32 v[94:95], v[94:95], s[80:81], 1.0 op_sel_hi:[1,0,0]
	v_pk_fma_f32 v[102:103], v[102:103], s[80:81], 1.0 op_sel_hi:[1,0,0]
	v_rcp_f32_e32 v226, v226
	v_rcp_f32_e32 v227, v227
	v_rcp_f32_e32 v234, v234
	v_rcp_f32_e32 v235, v235
	v_rcp_f32_e32 v94, v94
	v_rcp_f32_e32 v95, v95
	v_rcp_f32_e32 v102, v102
	v_rcp_f32_e32 v103, v103
	v_pk_fma_f32 v[228:229], v[226:227], s[50:51], v[248:249] op_sel_hi:[1,0,0]
	v_pk_fma_f32 v[236:237], v[234:235], s[50:51], v[248:249] op_sel_hi:[1,0,0]
	v_pk_fma_f32 v[96:97], v[94:95], s[50:51], v[248:249] op_sel_hi:[1,0,0]
	v_pk_fma_f32 v[88:89], v[102:103], s[50:51], v[248:249] op_sel_hi:[1,0,0]
	v_pk_fma_f32 v[228:229], v[226:227], v[228:229], s[76:77] op_sel_hi:[1,1,0]
	v_pk_fma_f32 v[236:237], v[234:235], v[236:237], s[76:77] op_sel_hi:[1,1,0]
	v_pk_fma_f32 v[96:97], v[94:95], v[96:97], s[76:77] op_sel_hi:[1,1,0]
	v_pk_fma_f32 v[88:89], v[102:103], v[88:89], s[76:77] op_sel_hi:[1,1,0]
	v_pk_fma_f32 v[228:229], v[226:227], v[228:229], s[78:79] op_sel_hi:[1,1,0]
	v_pk_fma_f32 v[236:237], v[234:235], v[236:237], s[78:79] op_sel_hi:[1,1,0]
	v_pk_fma_f32 v[96:97], v[94:95], v[96:97], s[78:79] op_sel_hi:[1,1,0]
	v_pk_fma_f32 v[88:89], v[102:103], v[88:89], s[78:79] op_sel_hi:[1,1,0]
	v_pk_fma_f32 v[228:229], v[226:227], v[228:229], s[2:3] op_sel_hi:[1,1,0]
	v_pk_fma_f32 v[236:237], v[234:235], v[236:237], s[2:3] op_sel_hi:[1,1,0]
	v_pk_fma_f32 v[96:97], v[94:95], v[96:97], s[2:3] op_sel_hi:[1,1,0]
	v_pk_fma_f32 v[88:89], v[102:103], v[88:89], s[2:3] op_sel_hi:[1,1,0]
	v_pk_mul_f32 v[226:227], v[226:227], v[228:229]
	v_pk_mul_f32 v[234:235], v[234:235], v[236:237]
	v_pk_mul_f32 v[94:95], v[94:95], v[96:97]
	v_pk_mul_f32 v[102:103], v[102:103], v[88:89]
	v_pk_mul_f32 v[230:231], v[224:225], v[224:225]
	v_pk_mul_f32 v[238:239], v[232:233], v[232:233]
	v_pk_mul_f32 v[98:99], v[92:93], v[92:93]
	v_pk_mul_f32 v[90:91], v[100:101], v[100:101]
	v_pk_mul_f32 v[230:231], v[230:231], s[0:1] op_sel_hi:[1,0]
	v_pk_mul_f32 v[238:239], v[238:239], s[0:1] op_sel_hi:[1,0]
	v_pk_mul_f32 v[98:99], v[98:99], s[0:1] op_sel_hi:[1,0]
	v_pk_mul_f32 v[90:91], v[90:91], s[0:1] op_sel_hi:[1,0]
	v_exp_f32_e32 v230, v230
	v_exp_f32_e32 v231, v231
	v_exp_f32_e32 v238, v238
	v_exp_f32_e32 v239, v239
	v_exp_f32_e32 v98, v98
	v_exp_f32_e32 v99, v99
	v_exp_f32_e32 v90, v90
	v_exp_f32_e32 v91, v91
	v_pk_mul_f32 v[226:227], v[230:231], v[226:227]
	v_pk_mul_f32 v[234:235], v[238:239], v[234:235]
	v_pk_mul_f32 v[94:95], v[98:99], v[94:95]
	v_pk_mul_f32 v[102:103], v[90:91], v[102:103]
	v_pk_mul_f32 v[228:229], v[224:225], v[226:227]
	v_pk_mul_f32 v[236:237], v[232:233], v[234:235]
	v_pk_mul_f32 v[96:97], v[92:93], v[94:95]
	v_pk_mul_f32 v[88:89], v[100:101], v[102:103]
	v_pk_fma_f32 v[230:231], v[224:225], v[226:227], v[224:225] neg_lo:[1,0,0] neg_hi:[1,0,0]
	v_pk_fma_f32 v[238:239], v[232:233], v[234:235], v[232:233] neg_lo:[1,0,0] neg_hi:[1,0,0]
	v_pk_fma_f32 v[98:99], v[92:93], v[94:95], v[92:93] neg_lo:[1,0,0] neg_hi:[1,0,0]
	v_pk_fma_f32 v[90:91], v[100:101], v[102:103], v[100:101] neg_lo:[1,0,0] neg_hi:[1,0,0]
	v_cmp_gt_f32_e64 s[98:99], 0, v224
	v_cmp_gt_f32_e64 s[100:101], 0, v225
	s_nop 1
	v_cndmask_b32_e64 v228, v230, v228, s[98:99]
	v_cndmask_b32_e64 v229, v231, v229, s[100:101]
	v_cmp_gt_f32_e64 s[98:99], 0, v232
	v_cmp_gt_f32_e64 s[100:101], 0, v233
	s_nop 1
	v_cndmask_b32_e64 v236, v238, v236, s[98:99]
	v_cndmask_b32_e64 v237, v239, v237, s[100:101]
	v_cmp_gt_f32_e64 s[98:99], 0, v92
	v_cmp_gt_f32_e64 s[100:101], 0, v93
	s_nop 1
	v_cndmask_b32_e64 v96, v98, v96, s[98:99]
	v_cndmask_b32_e64 v97, v99, v97, s[100:101]
	v_cmp_gt_f32_e64 s[98:99], 0, v100
	v_cmp_gt_f32_e64 s[100:101], 0, v101
	s_nop 1
	v_cndmask_b32_e64 v88, v90, v88, s[98:99]
	v_cndmask_b32_e64 v89, v91, v89, s[100:101]
	v_cvt_pk_bf16_f32 v240, v228, v229
	v_cvt_pk_bf16_f32 v241, v236, v237
	v_cvt_pk_bf16_f32 v242, v96, v97
	v_cvt_pk_bf16_f32 v243, v88, v89
	v_lshl_add_u64 v[244:245], v[108:109], 0, s[4:5]
	v_lshl_add_u64 v[250:251], v[106:107], 0, s[4:5]
	v_mbcnt_lo_u32_b32 v246, -1, 0
	v_mbcnt_hi_u32_b32 v246, -1, v246
	v_and_b32_e32 v246, 16, v246
	v_cmp_ne_u32_e32 vcc, 0, v246
	v_permlane16_swap_b32_e32 v240, v242
	v_permlane16_swap_b32_e32 v241, v243
	v_cndmask_b32_e32 v244, v244, v250, vcc
	v_cndmask_b32_e32 v245, v245, v251, vcc
	v_lshrrev_b32_e32 v246, 1, v246
	v_sub_co_u32_e32 v244, vcc, v244, v246
	v_subbrev_co_u32_e32 v245, vcc, 0, v245, vcc
	s_add_u32 s4, s4, 0x100000
	s_addc_u32 s5, s5, 0
	s_cmp_eq_u32 s4, 0x400000
	global_store_dwordx4 v[244:245], v[240:243], off
	s_cbranch_scc1 .LBB0_1391
